# flag barrier: arrival store issued before the two LDS reads; two poll loads kept in flight (no sleep)
# baseline (speedup 1.0000x reference)
.LBB0_507:
	s_cmp_eq_u32 s80, 27
	s_cbranch_scc1 .LBB0_222
	s_waitcnt vmcnt(0)
	s_waitcnt vmcnt(0) lgkmcnt(0)
	s_barrier
	s_mov_b64 s[0:1], exec
	v_readlane_b32 s2, v249, 2
	v_readlane_b32 s3, v249, 3
	s_and_b64 s[2:3], s[0:1], s[2:3]
	s_mov_b64 exec, s[2:3]
	s_cbranch_execz .LBB0_221
	v_readlane_b32 s2, v249, 4
	s_lshl_b32 s2, s2, 2
	s_add_u32 s2, s20, s2
	v_readlane_b32 s4, v247, 19
	s_addc_u32 s3, s21, 0
	s_waitcnt vmcnt(0) expcnt(0) lgkmcnt(0)
	v_mov_b32_e32 v0, s4
	ds_read_b32 v3, v0
	s_add_u32 s4, s2, 0x5e04000
	v_readlane_b32 s2, v247, 20
	s_addc_u32 s5, s3, 0
	s_add_i32 s8, s80, 1
	s_lshl_b32 s9, s33, 2
	s_add_u32 s22, s4, 0x3800
	s_addc_u32 s23, s5, 0
	s_add_u32 s24, s22, s9
	s_addc_u32 s25, s23, 0
	v_mov_b32_e32 v4, s8
	global_store_dword v2, v4, s[24:25]
	s_waitcnt lgkmcnt(0)
	v_cmp_ne_u32_e32 vcc, 0, v3
	v_mov_b32_e32 v0, s2
	ds_read_b32 v0, v0
	s_cbranch_vccnz .LBB0_524
	s_add_u32 s2, s4, 0x1000
	s_addc_u32 s3, s5, 0
	s_add_u32 s20, s4, 0x1100
	s_addc_u32 s21, s5, 0
	s_add_u32 s22, s4, 0x1200
	s_addc_u32 s23, s5, 0
	s_add_u32 s24, s4, 0x1300
	s_addc_u32 s25, s5, 0
	s_mov_b32 s8, 1
	s_branch .LBB0_512

.LBB0_524:
	s_waitcnt lgkmcnt(0)
	v_cmp_eq_u32_e32 vcc, 1, v0
	v_cmp_eq_u32_e64 s[22:23], s68, v3
	s_and_b64 vcc, vcc, s[22:23]
	s_cbranch_vccz .Lxb_slow
	s_add_i32 s8, s80, 1
	s_add_u32 s22, s4, 0x3800
	s_addc_u32 s23, s5, 0
	s_mov_b32 exec_lo, -1
	s_mov_b32 exec_hi, 0
	v_mbcnt_lo_u32_b32 v5, -1, 0
	v_lshlrev_b32_e32 v5, 2, v5
	global_load_dword v6, v5, s[22:23] sc1
.Lxb_poll:
	global_load_dword v7, v5, s[22:23] sc1
	s_waitcnt vmcnt(1)
	v_cmp_gt_u32_e32 vcc, s8, v6
	s_cbranch_vccz .Lxb_acq
	global_load_dword v6, v5, s[22:23] sc1
	s_waitcnt vmcnt(1)
	v_cmp_gt_u32_e32 vcc, s8, v7
	s_cbranch_vccz .Lxb_acq
	s_branch .Lxb_poll
